# gate/up K loop: phase-5 B fragment (4 ds_read_b128) read one phase earlier in phase 4's read-free section, K-tile retired earlier by vmcnt(10) at phase 3
# baseline (speedup 1.0000x reference)
; #define PG8_STAGE(bufoff, gbase, voff) do { _Pragma("unroll") for (int _i = 0; _i < 2; ++_i) \
;     __builtin_amdgcn_global_load_lds((const unsigned*)((const char*)(gbase) + (voff)[_i]), (LAS unsigned*)(lds + (bufoff) + ldsw + _i * 8192), 16, 0, 0); } while (0)
; #define PG8_LDA(dst, b, h) do { _Pragma("unroll") for (int m = 0; m < 4; ++m) _Pragma("unroll") for (int k = 0; k < 2; ++k) dst[m][k] = *(const LAS bf16x8*)(lds + PG8_SA(b, h) + aoff + m * 2048 + k * 1024); } while (0)
; #define PG8_LDB(dst, b, h) do { _Pragma("unroll") for (int n = 0; n < 2; ++n) _Pragma("unroll") for (int k = 0; k < 2; ++k) dst[n][k] = *(const LAS bf16x8*)(lds + PG8_SB(b, h) + boff + n * 2048 + k * 1024); } while (0)
; #define PG8_MMA(ai, bj, At, Bt) do { __builtin_amdgcn_s_setprio(1); _Pragma("unroll") for (int m = 0; m < 4; ++m) _Pragma("unroll") for (int n = 0; n < 2; ++n) _Pragma("unroll") for (int k = 0; k < 2; ++k) \
;     acc[ai][bj][m][n] = __builtin_amdgcn_mfma_f32_16x16x32_bf16(Bt[n][k], At[m][k], acc[ai][bj][m][n], 0, 0, 0); __builtin_amdgcn_s_setprio(0); } while (0)
; #define PG8_WAIT_L(n) asm volatile("s_waitcnt lgkmcnt(" #n ")" ::: "memory")
; #define PG8_BAR __builtin_amdgcn_s_barrier()
; #define PG8_SCHED __builtin_amdgcn_sched_barrier(0)
; template <class Epi, class Sched>
; DI void gemm_phase(LAS unsigned char* lds, const Gemm g, const Sched& S, const Epi& E) {
;     ...
;       const bool last = (t == nt - 2);
;       const char* a1 = cA + (size_t)(t + 1) * kstep;
;       const char* a2 = last ? nA : cA + (size_t)(t + 2) * kstep; const char* b2 = last ? nB : cB + (size_t)(t + 2) * kstep;
;       const char* a3 = a2 + kstep; const char* b3 = b2 + kstep;
;       PG8_LDB(B0, 0, 0); PG8_SCHED; PG8_LDA(At, 0, 0); PG8_STAGE(PG8_SA(1, 1), a1 + hstep, voffA);
;       PG8_WAIT_L(8); PG8_BAR; PG8_WAIT_L(0); PG8_MMA(0, 0, At, B0); PG8_BAR; PG8_SCHED;
;       PG8_LDB(B1, 0, 1); PG8_STAGE(PG8_SB(0, 0), b2, voffB);
;       PG8_BAR; PG8_WAIT_L(0); PG8_MMA(0, 1, At, B1); PG8_BAR;
;       PG8_LDA(At, 0, 1); PG8_STAGE(PG8_SA(0, 0), a2, voffA);
;       PG8_BAR; PG8_WAIT_L(0); PG8_MMA(1, 0, At, B0); PG8_BAR; PG8_SCHED;
.LBB0_178:
	s_add_i32 s51, s24, 2
	s_add_u32 s26, s22, 0x80
	s_addc_u32 s25, s23, 0
	s_add_i32 s52, 16, 0x10000
	v_add_u32_e32 v156, s52, v141
	ds_read_b128 v[144:147], v156
	ds_read_b128 v[148:151], v156 offset:1024
	ds_read_b128 v[152:155], v156 offset:2048
	ds_read_b128 v[156:159], v156 offset:3072
	s_cmp_eq_u32 s43, s24
	s_cselect_b32 s24, s18, s26
	s_cselect_b32 s25, s19, s25
	s_cselect_b32 s27, s21, s50
	s_cselect_b32 s26, s20, s49
	v_lshl_add_u64 v[176:177], s[22:23], 0, v[136:137]
	s_add_i32 m0, s36, 0xc000
	ds_read_b128 v[160:163], v143
	ds_read_b128 v[164:167], v143 offset:1024
	ds_read_b128 v[168:171], v143 offset:2048
	ds_read_b128 v[172:175], v143 offset:3072
	ds_read_b128 v[186:189], v143 offset:4096
	ds_read_b128 v[190:193], v143 offset:5120
	ds_read_b128 v[198:201], v143 offset:6144
	ds_read_b128 v[202:205], v143 offset:7168
	global_load_lds_dwordx4 v[176:177], off
	v_lshl_add_u64 v[176:177], s[22:23], 0, v[138:139]
	s_add_i32 m0, s36, 0xe000
	s_nop 0
	global_load_lds_dwordx4 v[176:177], off
	s_waitcnt lgkmcnt(8)
	s_barrier
	s_waitcnt lgkmcnt(0)
	s_waitcnt lgkmcnt(0)
	v_mfma_f32_16x16x32_bf16 v[122:125], v[144:147], v[160:163], v[122:125]
	v_mfma_f32_16x16x32_bf16 v[118:121], v[152:155], v[160:163], v[118:121]
	v_mfma_f32_16x16x32_bf16 v[110:113], v[144:147], v[168:171], v[110:113]
	v_mfma_f32_16x16x32_bf16 v[102:105], v[152:155], v[168:171], v[102:105]
	v_mfma_f32_16x16x32_bf16 v[94:97], v[144:147], v[186:189], v[94:97]
	v_mfma_f32_16x16x32_bf16 v[86:89], v[152:155], v[186:189], v[86:89]
	v_mfma_f32_16x16x32_bf16 v[78:81], v[144:147], v[198:201], v[78:81]
	v_mfma_f32_16x16x32_bf16 v[70:73], v[152:155], v[198:201], v[70:73]
	v_mfma_f32_16x16x32_bf16 v[122:125], v[148:151], v[164:167], v[122:125]
	v_mfma_f32_16x16x32_bf16 v[118:121], v[156:159], v[164:167], v[118:121]
	v_mfma_f32_16x16x32_bf16 v[110:113], v[148:151], v[172:175], v[110:113]
	v_mfma_f32_16x16x32_bf16 v[102:105], v[156:159], v[172:175], v[102:105]
	v_mfma_f32_16x16x32_bf16 v[94:97], v[148:151], v[190:193], v[94:97]
	v_mfma_f32_16x16x32_bf16 v[86:89], v[156:159], v[190:193], v[86:89]
	v_mfma_f32_16x16x32_bf16 v[78:81], v[148:151], v[202:205], v[78:81]
	v_mfma_f32_16x16x32_bf16 v[70:73], v[156:159], v[202:205], v[70:73]
	s_barrier
	s_add_i32 s53, 16, 0x14000
	v_add_u32_e32 v176, s53, v141
	s_add_i32 s52, s52, s35
	ds_read_b128 v[206:209], v176
	ds_read_b128 v[214:217], v176 offset:1024
	ds_read_b128 v[218:221], v176 offset:2048
	ds_read_b128 v[222:225], v176 offset:3072
	v_lshl_add_u64 v[176:177], s[26:27], 0, v[0:1]
	s_mov_b32 m0, s52
	v_lshl_add_u64 v[180:181], s[26:27], 0, v[130:131]
	global_load_lds_dwordx4 v[176:177], off
	s_add_i32 m0, s52, 0x2000
	s_nop 0
	global_load_lds_dwordx4 v[180:181], off
	s_barrier
	s_waitcnt lgkmcnt(0)
	s_waitcnt lgkmcnt(0)
	v_mfma_f32_16x16x32_bf16 v[126:129], v[206:209], v[160:163], v[126:129]
	v_mfma_f32_16x16x32_bf16 v[114:117], v[218:221], v[160:163], v[114:117]
	v_mfma_f32_16x16x32_bf16 v[106:109], v[206:209], v[168:171], v[106:109]
	v_mfma_f32_16x16x32_bf16 v[98:101], v[218:221], v[168:171], v[98:101]
	v_mfma_f32_16x16x32_bf16 v[90:93], v[206:209], v[186:189], v[90:93]
	v_mfma_f32_16x16x32_bf16 v[82:85], v[218:221], v[186:189], v[82:85]
	v_mfma_f32_16x16x32_bf16 v[74:77], v[206:209], v[198:201], v[74:77]
	v_mfma_f32_16x16x32_bf16 v[66:69], v[218:221], v[198:201], v[66:69]
	v_mfma_f32_16x16x32_bf16 v[126:129], v[214:217], v[164:167], v[126:129]
	v_mfma_f32_16x16x32_bf16 v[114:117], v[222:225], v[164:167], v[114:117]
	v_mfma_f32_16x16x32_bf16 v[106:109], v[214:217], v[172:175], v[106:109]
	v_mfma_f32_16x16x32_bf16 v[98:101], v[222:225], v[172:175], v[98:101]
	v_mfma_f32_16x16x32_bf16 v[90:93], v[214:217], v[190:193], v[90:93]
	v_mfma_f32_16x16x32_bf16 v[82:85], v[222:225], v[190:193], v[82:85]
	v_mfma_f32_16x16x32_bf16 v[74:77], v[214:217], v[202:205], v[74:77]
	v_mfma_f32_16x16x32_bf16 v[66:69], v[222:225], v[202:205], v[66:69]
	s_mov_b32 m0, s36
	v_lshl_add_u64 v[182:183], s[24:25], 0, v[134:135]
	s_barrier
	ds_read_b128 v[160:163], v143 offset:16384
	ds_read_b128 v[164:167], v143 offset:17408
	ds_read_b128 v[168:171], v143 offset:18432
	ds_read_b128 v[172:175], v143 offset:19456
	ds_read_b128 v[186:189], v143 offset:20480
	ds_read_b128 v[190:193], v143 offset:21504
	ds_read_b128 v[198:201], v143 offset:22528
	ds_read_b128 v[202:205], v143 offset:23552
	global_load_lds_dwordx4 v[182:183], off
	v_lshl_add_u64 v[184:185], s[24:25], 0, v[132:133]
	s_mov_b32 m0, s37
	s_nop 0
	global_load_lds_dwordx4 v[184:185], off
	s_waitcnt vmcnt(10)
	s_barrier
	s_waitcnt lgkmcnt(0)
	s_waitcnt lgkmcnt(0)
	v_mfma_f32_16x16x32_bf16 v[62:65], v[144:147], v[160:163], v[62:65]
	v_mfma_f32_16x16x32_bf16 v[54:57], v[152:155], v[160:163], v[54:57]
	v_mfma_f32_16x16x32_bf16 v[46:49], v[144:147], v[168:171], v[46:49]
	v_mfma_f32_16x16x32_bf16 v[38:41], v[152:155], v[168:171], v[38:41]
	v_mfma_f32_16x16x32_bf16 v[30:33], v[144:147], v[186:189], v[30:33]
	v_mfma_f32_16x16x32_bf16 v[22:25], v[152:155], v[186:189], v[22:25]
	v_mfma_f32_16x16x32_bf16 v[14:17], v[144:147], v[198:201], v[14:17]
	v_mfma_f32_16x16x32_bf16 v[6:9], v[152:155], v[198:201], v[6:9]
	v_mfma_f32_16x16x32_bf16 v[62:65], v[148:151], v[164:167], v[62:65]
	v_mfma_f32_16x16x32_bf16 v[54:57], v[156:159], v[164:167], v[54:57]
	v_mfma_f32_16x16x32_bf16 v[46:49], v[148:151], v[172:175], v[46:49]
	v_mfma_f32_16x16x32_bf16 v[38:41], v[156:159], v[172:175], v[38:41]
	v_mfma_f32_16x16x32_bf16 v[30:33], v[148:151], v[190:193], v[30:33]
	v_mfma_f32_16x16x32_bf16 v[22:25], v[156:159], v[190:193], v[22:25]
	v_mfma_f32_16x16x32_bf16 v[14:17], v[148:151], v[202:205], v[14:17]
	v_mfma_f32_16x16x32_bf16 v[6:9], v[156:159], v[202:205], v[6:9]
	s_barrier
; #define PG8_STAGE(bufoff, gbase, voff) do { _Pragma("unroll") for (int _i = 0; _i < 2; ++_i) \
;     __builtin_amdgcn_global_load_lds((const unsigned*)((const char*)(gbase) + (voff)[_i]), (LAS unsigned*)(lds + (bufoff) + ldsw + _i * 8192), 16, 0, 0); } while (0)
; #define PG8_LDA(dst, b, h) do { _Pragma("unroll") for (int m = 0; m < 4; ++m) _Pragma("unroll") for (int k = 0; k < 2; ++k) dst[m][k] = *(const LAS bf16x8*)(lds + PG8_SA(b, h) + aoff + m * 2048 + k * 1024); } while (0)
; #define PG8_LDB(dst, b, h) do { _Pragma("unroll") for (int n = 0; n < 2; ++n) _Pragma("unroll") for (int k = 0; k < 2; ++k) dst[n][k] = *(const LAS bf16x8*)(lds + PG8_SB(b, h) + boff + n * 2048 + k * 1024); } while (0)
; #define PG8_MMA(ai, bj, At, Bt) do { __builtin_amdgcn_s_setprio(1); _Pragma("unroll") for (int m = 0; m < 4; ++m) _Pragma("unroll") for (int n = 0; n < 2; ++n) _Pragma("unroll") for (int k = 0; k < 2; ++k) \
;     acc[ai][bj][m][n] = __builtin_amdgcn_mfma_f32_16x16x32_bf16(Bt[n][k], At[m][k], acc[ai][bj][m][n], 0, 0, 0); __builtin_amdgcn_s_setprio(0); } while (0)
; #define PG8_WAIT_V(n) asm volatile("s_waitcnt vmcnt(" #n ")" ::: "memory")
; #define PG8_WAIT_L(n) asm volatile("s_waitcnt lgkmcnt(" #n ")" ::: "memory")
; #define PG8_BAR __builtin_amdgcn_s_barrier()
; #define PG8_SCHED __builtin_amdgcn_sched_barrier(0)
; template <class Epi, class Sched>
; DI void gemm_phase(LAS unsigned char* lds, const Gemm g, const Sched& S, const Epi& E) {
;     ...
;       PG8_STAGE(PG8_SB(0, 1), b2 + hstepB, voffB);
;       PG8_WAIT_V(6); PG8_BAR; PG8_MMA(1, 1, At, B1); PG8_BAR;
;       PG8_LDB(B0, 1, 0); PG8_SCHED; PG8_LDA(At, 1, 0); PG8_STAGE(PG8_SA(0, 1), a2 + hstep, voffA);
;       PG8_WAIT_L(8); PG8_BAR; PG8_WAIT_L(0); PG8_MMA(0, 0, At, B0); PG8_BAR; PG8_SCHED;
;       PG8_LDB(B1, 1, 1); PG8_STAGE(PG8_SB(1, 0), b3, voffB);
;       PG8_BAR; PG8_WAIT_L(0); PG8_MMA(0, 1, At, B1); PG8_BAR;
	v_add_u32_e32 v156, 0x18010, v141
	ds_read_b128 v[144:147], v156
	ds_read_b128 v[148:151], v156 offset:1024
	ds_read_b128 v[152:155], v156 offset:2048
	ds_read_b128 v[156:159], v156 offset:3072
	s_add_u32 s26, s26, s0
	s_addc_u32 s27, s27, s1
	s_add_i32 s52, s53, s35
	v_lshl_add_u64 v[226:227], s[26:27], 0, v[0:1]
	s_mov_b32 m0, s52
	v_lshl_add_u64 v[228:229], s[26:27], 0, v[130:131]
	global_load_lds_dwordx4 v[226:227], off
	s_add_i32 m0, s52, 0x2000
	s_nop 0
	global_load_lds_dwordx4 v[228:229], off
	s_waitcnt vmcnt(6)
	s_barrier
	v_mfma_f32_16x16x32_bf16 v[58:61], v[206:209], v[160:163], v[58:61]
	v_mfma_f32_16x16x32_bf16 v[50:53], v[218:221], v[160:163], v[50:53]
	v_mfma_f32_16x16x32_bf16 v[42:45], v[206:209], v[168:171], v[42:45]
	v_mfma_f32_16x16x32_bf16 v[34:37], v[218:221], v[168:171], v[34:37]
	v_mfma_f32_16x16x32_bf16 v[26:29], v[206:209], v[186:189], v[26:29]
	v_mfma_f32_16x16x32_bf16 v[18:21], v[218:221], v[186:189], v[18:21]
	v_mfma_f32_16x16x32_bf16 v[10:13], v[206:209], v[198:201], v[10:13]
	v_mfma_f32_16x16x32_bf16 v[2:5], v[218:221], v[198:201], v[2:5]
	v_mfma_f32_16x16x32_bf16 v[58:61], v[214:217], v[164:167], v[58:61]
	v_mfma_f32_16x16x32_bf16 v[50:53], v[222:225], v[164:167], v[50:53]
	v_mfma_f32_16x16x32_bf16 v[42:45], v[214:217], v[172:175], v[42:45]
	v_mfma_f32_16x16x32_bf16 v[34:37], v[222:225], v[172:175], v[34:37]
	v_mfma_f32_16x16x32_bf16 v[26:29], v[214:217], v[190:193], v[26:29]
	v_mfma_f32_16x16x32_bf16 v[18:21], v[222:225], v[190:193], v[18:21]
	v_mfma_f32_16x16x32_bf16 v[10:13], v[214:217], v[202:205], v[10:13]
	v_mfma_f32_16x16x32_bf16 v[2:5], v[222:225], v[202:205], v[2:5]
	s_add_i32 s26, 16, 0x18000
	s_barrier
	s_add_u32 s24, s24, s0
	s_addc_u32 s25, s25, s1
	s_mov_b32 m0, s38
	v_lshl_add_u64 v[206:207], s[24:25], 0, v[134:135]
	ds_read_b128 v[160:163], v143 offset:32768
	ds_read_b128 v[164:167], v143 offset:33792
	ds_read_b128 v[168:171], v143 offset:34816
	ds_read_b128 v[172:175], v143 offset:35840
	ds_read_b128 v[186:189], v143 offset:36864
	ds_read_b128 v[190:193], v143 offset:37888
	ds_read_b128 v[198:201], v143 offset:38912
	ds_read_b128 v[202:205], v143 offset:39936
	global_load_lds_dwordx4 v[206:207], off
	v_lshl_add_u64 v[206:207], s[24:25], 0, v[132:133]
	s_mov_b32 m0, s39
	s_nop 0
	global_load_lds_dwordx4 v[206:207], off
	s_waitcnt lgkmcnt(8)
	s_barrier
	s_waitcnt lgkmcnt(0)
	s_waitcnt lgkmcnt(0)
	v_mfma_f32_16x16x32_bf16 v[122:125], v[144:147], v[160:163], v[122:125]
	v_mfma_f32_16x16x32_bf16 v[118:121], v[152:155], v[160:163], v[118:121]
	v_mfma_f32_16x16x32_bf16 v[110:113], v[144:147], v[168:171], v[110:113]
	v_mfma_f32_16x16x32_bf16 v[102:105], v[152:155], v[168:171], v[102:105]
	v_mfma_f32_16x16x32_bf16 v[94:97], v[144:147], v[186:189], v[94:97]
	v_mfma_f32_16x16x32_bf16 v[86:89], v[152:155], v[186:189], v[86:89]
	v_mfma_f32_16x16x32_bf16 v[78:81], v[144:147], v[198:201], v[78:81]
	v_mfma_f32_16x16x32_bf16 v[70:73], v[152:155], v[198:201], v[70:73]
	v_mfma_f32_16x16x32_bf16 v[122:125], v[148:151], v[164:167], v[122:125]
	v_mfma_f32_16x16x32_bf16 v[118:121], v[156:159], v[164:167], v[118:121]
	v_mfma_f32_16x16x32_bf16 v[110:113], v[148:151], v[172:175], v[110:113]
	v_mfma_f32_16x16x32_bf16 v[102:105], v[156:159], v[172:175], v[102:105]
	v_mfma_f32_16x16x32_bf16 v[94:97], v[148:151], v[190:193], v[94:97]
	v_mfma_f32_16x16x32_bf16 v[86:89], v[156:159], v[190:193], v[86:89]
	v_mfma_f32_16x16x32_bf16 v[78:81], v[148:151], v[202:205], v[78:81]
	v_mfma_f32_16x16x32_bf16 v[70:73], v[156:159], v[202:205], v[70:73]
	s_barrier
	s_add_i32 s24, 16, 0x1c000
	s_add_i32 s25, s26, s35
	v_add_u32_e32 v194, s24, v141
	v_lshl_add_u64 v[176:177], v[176:177], 0, s[70:71]
	s_mov_b32 m0, s25
	ds_read_b128 v[206:209], v194
	ds_read_b128 v[214:217], v194 offset:1024
	ds_read_b128 v[218:221], v194 offset:2048
	ds_read_b128 v[222:225], v194 offset:3072
	global_load_lds_dwordx4 v[176:177], off
	v_lshl_add_u64 v[176:177], v[180:181], 0, s[70:71]
	s_add_i32 m0, s25, 0x2000
	s_nop 0
	global_load_lds_dwordx4 v[176:177], off
	s_barrier
; #define PG8_STAGE(bufoff, gbase, voff) do { _Pragma("unroll") for (int _i = 0; _i < 2; ++_i) \
;     __builtin_amdgcn_global_load_lds((const unsigned*)((const char*)(gbase) + (voff)[_i]), (LAS unsigned*)(lds + (bufoff) + ldsw + _i * 8192), 16, 0, 0); } while (0)
; #define PG8_LDA(dst, b, h) do { _Pragma("unroll") for (int m = 0; m < 4; ++m) _Pragma("unroll") for (int k = 0; k < 2; ++k) dst[m][k] = *(const LAS bf16x8*)(lds + PG8_SA(b, h) + aoff + m * 2048 + k * 1024); } while (0)
; #define PG8_MMA(ai, bj, At, Bt) do { __builtin_amdgcn_s_setprio(1); _Pragma("unroll") for (int m = 0; m < 4; ++m) _Pragma("unroll") for (int n = 0; n < 2; ++n) _Pragma("unroll") for (int k = 0; k < 2; ++k) \
;     acc[ai][bj][m][n] = __builtin_amdgcn_mfma_f32_16x16x32_bf16(Bt[n][k], At[m][k], acc[ai][bj][m][n], 0, 0, 0); __builtin_amdgcn_s_setprio(0); } while (0)
; #define PG8_WAIT_V(n) asm volatile("s_waitcnt vmcnt(" #n ")" ::: "memory")
; #define PG8_WAIT_L(n) asm volatile("s_waitcnt lgkmcnt(" #n ")" ::: "memory")
; #define PG8_BAR __builtin_amdgcn_s_barrier()
; #define PG8_SCHED __builtin_amdgcn_sched_barrier(0)
; template <class Epi, class Sched>
; DI void gemm_phase(LAS unsigned char* lds, const Gemm g, const Sched& S, const Epi& E) {
;     ...
;       PG8_BAR; PG8_WAIT_L(0); PG8_MMA(0, 1, At, B1); PG8_BAR;
;       PG8_LDA(At, 1, 1); PG8_STAGE(PG8_SA(1, 0), a3, voffA);
;       PG8_BAR; PG8_WAIT_L(0); PG8_MMA(1, 0, At, B0); PG8_BAR; PG8_SCHED;
;       PG8_STAGE(PG8_SB(1, 1), b3 + hstepB, voffB);
;       PG8_WAIT_V(6); PG8_BAR; PG8_MMA(1, 1, At, B1); PG8_BAR;
;     }
	s_waitcnt lgkmcnt(0)
	s_waitcnt lgkmcnt(0)
	v_mfma_f32_16x16x32_bf16 v[126:129], v[206:209], v[160:163], v[126:129]
	v_mfma_f32_16x16x32_bf16 v[114:117], v[218:221], v[160:163], v[114:117]
	v_mfma_f32_16x16x32_bf16 v[106:109], v[206:209], v[168:171], v[106:109]
	v_mfma_f32_16x16x32_bf16 v[98:101], v[218:221], v[168:171], v[98:101]
	v_mfma_f32_16x16x32_bf16 v[90:93], v[206:209], v[186:189], v[90:93]
	v_mfma_f32_16x16x32_bf16 v[82:85], v[218:221], v[186:189], v[82:85]
	v_mfma_f32_16x16x32_bf16 v[74:77], v[206:209], v[198:201], v[74:77]
	v_mfma_f32_16x16x32_bf16 v[66:69], v[218:221], v[198:201], v[66:69]
	v_mfma_f32_16x16x32_bf16 v[126:129], v[214:217], v[164:167], v[126:129]
	v_mfma_f32_16x16x32_bf16 v[114:117], v[222:225], v[164:167], v[114:117]
	v_mfma_f32_16x16x32_bf16 v[106:109], v[214:217], v[172:175], v[106:109]
	v_mfma_f32_16x16x32_bf16 v[98:101], v[222:225], v[172:175], v[98:101]
	v_mfma_f32_16x16x32_bf16 v[90:93], v[214:217], v[190:193], v[90:93]
	v_mfma_f32_16x16x32_bf16 v[82:85], v[222:225], v[190:193], v[82:85]
	v_mfma_f32_16x16x32_bf16 v[74:77], v[214:217], v[202:205], v[74:77]
	v_mfma_f32_16x16x32_bf16 v[66:69], v[222:225], v[202:205], v[66:69]
	s_mov_b32 m0, s41
	v_lshl_add_u64 v[176:177], v[182:183], 0, s[70:71]
	s_barrier
	ds_read_b128 v[160:163], v143 offset:49152
	ds_read_b128 v[164:167], v143 offset:50176
	ds_read_b128 v[168:171], v143 offset:51200
	ds_read_b128 v[172:175], v143 offset:52224
	ds_read_b128 v[186:189], v143 offset:53248
	ds_read_b128 v[190:193], v143 offset:54272
	ds_read_b128 v[198:201], v143 offset:55296
	ds_read_b128 v[202:205], v143 offset:56320
	global_load_lds_dwordx4 v[176:177], off
	v_lshl_add_u64 v[176:177], v[184:185], 0, s[70:71]
	s_mov_b32 m0, s42
	s_nop 0
	global_load_lds_dwordx4 v[176:177], off
	s_barrier
	s_waitcnt lgkmcnt(0)
	s_waitcnt lgkmcnt(0)
	v_mfma_f32_16x16x32_bf16 v[62:65], v[144:147], v[160:163], v[62:65]
	v_mfma_f32_16x16x32_bf16 v[54:57], v[152:155], v[160:163], v[54:57]
	v_mfma_f32_16x16x32_bf16 v[46:49], v[144:147], v[168:171], v[46:49]
	v_mfma_f32_16x16x32_bf16 v[38:41], v[152:155], v[168:171], v[38:41]
	v_mfma_f32_16x16x32_bf16 v[30:33], v[144:147], v[186:189], v[30:33]
	v_mfma_f32_16x16x32_bf16 v[22:25], v[152:155], v[186:189], v[22:25]
	v_mfma_f32_16x16x32_bf16 v[14:17], v[144:147], v[198:201], v[14:17]
	v_mfma_f32_16x16x32_bf16 v[6:9], v[152:155], v[198:201], v[6:9]
	v_mfma_f32_16x16x32_bf16 v[62:65], v[148:151], v[164:167], v[62:65]
	v_mfma_f32_16x16x32_bf16 v[54:57], v[156:159], v[164:167], v[54:57]
	v_mfma_f32_16x16x32_bf16 v[46:49], v[148:151], v[172:175], v[46:49]
	v_mfma_f32_16x16x32_bf16 v[38:41], v[156:159], v[172:175], v[38:41]
	v_mfma_f32_16x16x32_bf16 v[30:33], v[148:151], v[190:193], v[30:33]
	v_mfma_f32_16x16x32_bf16 v[22:25], v[156:159], v[190:193], v[22:25]
	v_mfma_f32_16x16x32_bf16 v[14:17], v[148:151], v[202:205], v[14:17]
	v_mfma_f32_16x16x32_bf16 v[6:9], v[156:159], v[202:205], v[6:9]
	s_barrier
	s_add_i32 s24, s24, s35
	v_lshl_add_u64 v[144:145], v[226:227], 0, s[70:71]
	s_mov_b32 m0, s24
	s_nop 0
	global_load_lds_dwordx4 v[144:145], off
	v_lshl_add_u64 v[144:145], v[228:229], 0, s[70:71]
	s_add_i32 m0, s24, 0x2000
	s_nop 0
	global_load_lds_dwordx4 v[144:145], off
	s_waitcnt vmcnt(6)
	s_barrier
	v_mfma_f32_16x16x32_bf16 v[58:61], v[206:209], v[160:163], v[58:61]
	v_mfma_f32_16x16x32_bf16 v[50:53], v[218:221], v[160:163], v[50:53]
	v_mfma_f32_16x16x32_bf16 v[42:45], v[206:209], v[168:171], v[42:45]
	v_mfma_f32_16x16x32_bf16 v[34:37], v[218:221], v[168:171], v[34:37]
	v_mfma_f32_16x16x32_bf16 v[26:29], v[206:209], v[186:189], v[26:29]
	v_mfma_f32_16x16x32_bf16 v[18:21], v[218:221], v[186:189], v[18:21]
	v_mfma_f32_16x16x32_bf16 v[10:13], v[206:209], v[198:201], v[10:13]
	v_mfma_f32_16x16x32_bf16 v[2:5], v[218:221], v[198:201], v[2:5]
	v_mfma_f32_16x16x32_bf16 v[58:61], v[214:217], v[164:167], v[58:61]
	v_mfma_f32_16x16x32_bf16 v[50:53], v[222:225], v[164:167], v[50:53]
	v_mfma_f32_16x16x32_bf16 v[42:45], v[214:217], v[172:175], v[42:45]
	v_mfma_f32_16x16x32_bf16 v[34:37], v[222:225], v[172:175], v[34:37]
	v_mfma_f32_16x16x32_bf16 v[26:29], v[214:217], v[190:193], v[26:29]
	v_mfma_f32_16x16x32_bf16 v[18:21], v[222:225], v[190:193], v[18:21]
	v_mfma_f32_16x16x32_bf16 v[10:13], v[214:217], v[202:205], v[10:13]
	v_mfma_f32_16x16x32_bf16 v[2:5], v[222:225], v[202:205], v[2:5]
	s_add_u32 s22, s22, 0x100
	s_addc_u32 s23, s23, 0
	s_add_u32 s49, s49, 0x100
	s_addc_u32 s50, s50, 0
	s_cmp_ge_i32 s51, s40
	s_mov_b32 s24, s51
	s_barrier
	s_cbranch_scc0 .LBB0_178
	s_branch .LBB0_161
